# RWKV scan: per-step y partials kept for 16 steps and reduce-scattered across the 16 lanes instead of an all-reduce every step
# speedup vs baseline: 1.2884x; 1.0121x over previous
.Lscan_nostate:
	v_and_b32_e32 v38, 2, v36
	v_cmp_ne_u32_e64 s[36:37], 0, v38
	v_and_b32_e32 v38, 1, v36
	v_cmp_ne_u32_e64 s[38:39], 0, v38
	v_mov_b32_e32 v23, 0
	s_mov_b32 s6, 0
	s_mov_b32 s7, 21504
	s_mov_b32 s25, 43040
	v_mov_b32_e32 v139, v24
	v_mov_b32_e32 v140, v25
	v_add_u32_e32 v141, s7, v24
	v_add_u32_e32 v142, s7, v25
	v_add_u32_e32 v143, s7, v26
	v_add_u32_e32 v35, s7, v27
	s_cmp_lg_u32 s28, 0
	s_cbranch_scc1 .Lscan_w0
	s_waitcnt vmcnt(1)
	s_branch .Lscan_w1

.Lscan_chunk:
	v_pk_mul_f32 v[16:17], v[0:1], v[44:45]
	v_pk_mul_f32 v[20:21], v[0:1], v[122:123]
	ds_read_b128 v[96:99], v139 offset:3456
	v_pk_fma_f32 v[16:17], v[2:3], v[46:47], v[16:17]
	v_pk_fma_f32 v[20:21], v[2:3], v[124:125], v[20:21]
	ds_read_b32 v104, v140 offset:2688
	v_add_f32_e32 v18, v16, v17
	v_pk_fma_f32 v[4:5], v[0:1], v[40:41], v[8:9]
	v_add_f32_e32 v201, v20, v21
	v_add_f32_dpp v18, v18, v18 quad_perm:[1,0,3,2] row_mask:0xf bank_mask:0xf bound_ctrl:1
	v_pk_fma_f32 v[6:7], v[2:3], v[42:43], v[10:11]
	s_nop 0
	v_add_f32_dpp v18, v18, v18 quad_perm:[2,3,0,1] row_mask:0xf bank_mask:0xf bound_ctrl:1
	ds_read_b128 v[88:91], v139 offset:2944
	v_add_f32_dpp v201, v201, v201 row_ror:8 row_mask:0xf bank_mask:0xc bound_ctrl:1
	v_add_f32_dpp v18, v18, v18 row_half_mirror row_mask:0xf bank_mask:0xf bound_ctrl:1
	ds_read_b128 v[84:87], v139 offset:2688
	v_add_f32_dpp v201, v191, v191 row_ror:8 row_mask:0xf bank_mask:0x3 bound_ctrl:1
	v_add_f32_dpp v18, v18, v18 row_ror:8 row_mask:0xf bank_mask:0xf bound_ctrl:1
	ds_read_b128 v[92:95], v139 offset:3200
	v_pk_fma_f32 v[0:1], v[48:49], v[18:19], v[4:5] op_sel_hi:[1,0,1] neg_lo:[1,0,0] neg_hi:[1,0,0]
	v_pk_fma_f32 v[2:3], v[50:51], v[18:19], v[6:7] op_sel_hi:[1,0,1] neg_lo:[1,0,0] neg_hi:[1,0,0]
	ds_read_b128 v[100:103], v139 offset:3712
	s_waitcnt lgkmcnt(7)
	v_pk_mul_f32 v[8:9], v[74:75], v[82:83] op_sel_hi:[1,0]
	v_pk_mul_f32 v[10:11], v[76:77], v[82:83] op_sel_hi:[1,0]
	v_pk_mul_f32 v[16:17], v[0:1], v[66:67]
	v_pk_mul_f32 v[20:21], v[0:1], v[56:57]
	ds_read_b128 v[118:121], v139 offset:4800
	v_pk_fma_f32 v[16:17], v[2:3], v[68:69], v[16:17]
	v_pk_fma_f32 v[20:21], v[2:3], v[58:59], v[20:21]
	ds_read_b32 v126, v140 offset:4032
	v_add_f32_e32 v18, v16, v17
	v_pk_fma_f32 v[4:5], v[0:1], v[62:63], v[8:9]
	v_add_f32_e32 v12, v20, v21
	v_add_f32_dpp v18, v18, v18 quad_perm:[1,0,3,2] row_mask:0xf bank_mask:0xf bound_ctrl:1
	v_pk_fma_f32 v[6:7], v[2:3], v[64:65], v[10:11]
	v_add_f32_dpp v196, v196, v196 row_half_mirror row_mask:0xf bank_mask:0xa bound_ctrl:1
	v_add_f32_dpp v18, v18, v18 quad_perm:[2,3,0,1] row_mask:0xf bank_mask:0xf bound_ctrl:1
	ds_read_b128 v[110:113], v139 offset:4288
	v_add_f32_dpp v196, v192, v192 row_half_mirror row_mask:0xf bank_mask:0x5 bound_ctrl:1
	v_add_f32_dpp v18, v18, v18 row_half_mirror row_mask:0xf bank_mask:0xf bound_ctrl:1
	ds_read_b128 v[106:109], v139 offset:4032
	v_add_f32_dpp v197, v197, v197 row_half_mirror row_mask:0xf bank_mask:0xa bound_ctrl:1
	v_add_f32_dpp v18, v18, v18 row_ror:8 row_mask:0xf bank_mask:0xf bound_ctrl:1
	ds_read_b128 v[114:117], v139 offset:4544
	v_pk_fma_f32 v[0:1], v[70:71], v[18:19], v[4:5] op_sel_hi:[1,0,1] neg_lo:[1,0,0] neg_hi:[1,0,0]
	v_pk_fma_f32 v[2:3], v[72:73], v[18:19], v[6:7] op_sel_hi:[1,0,1] neg_lo:[1,0,0] neg_hi:[1,0,0]
	ds_read_b128 v[122:125], v139 offset:5056
	s_waitcnt lgkmcnt(7)
	v_pk_mul_f32 v[8:9], v[96:97], v[104:105] op_sel_hi:[1,0]
	v_pk_mul_f32 v[10:11], v[98:99], v[104:105] op_sel_hi:[1,0]
	v_pk_mul_f32 v[16:17], v[0:1], v[88:89]
	v_pk_mul_f32 v[20:21], v[0:1], v[78:79]
	ds_read_b128 v[52:55], v139 offset:6144
	v_pk_fma_f32 v[16:17], v[2:3], v[90:91], v[16:17]
	v_pk_fma_f32 v[20:21], v[2:3], v[80:81], v[20:21]
	ds_read_b32 v60, v140 offset:5376
	v_add_f32_e32 v18, v16, v17
	v_pk_fma_f32 v[4:5], v[0:1], v[84:85], v[8:9]
	v_add_f32_e32 v13, v20, v21
	v_add_f32_dpp v18, v18, v18 quad_perm:[1,0,3,2] row_mask:0xf bank_mask:0xf bound_ctrl:1
	v_pk_fma_f32 v[6:7], v[2:3], v[86:87], v[10:11]
	v_add_f32_dpp v197, v193, v193 row_half_mirror row_mask:0xf bank_mask:0x5 bound_ctrl:1
	v_add_f32_dpp v18, v18, v18 quad_perm:[2,3,0,1] row_mask:0xf bank_mask:0xf bound_ctrl:1
	ds_read_b128 v[44:47], v139 offset:5632
	v_add_f32_dpp v200, v200, v200 row_half_mirror row_mask:0xf bank_mask:0xa bound_ctrl:1
	v_add_f32_dpp v18, v18, v18 row_half_mirror row_mask:0xf bank_mask:0xf bound_ctrl:1
	ds_read_b128 v[40:43], v139 offset:5376
	v_add_f32_dpp v200, v194, v194 row_half_mirror row_mask:0xf bank_mask:0x5 bound_ctrl:1
	v_add_f32_dpp v18, v18, v18 row_ror:8 row_mask:0xf bank_mask:0xf bound_ctrl:1
	ds_read_b128 v[48:51], v139 offset:5888
	v_pk_fma_f32 v[0:1], v[92:93], v[18:19], v[4:5] op_sel_hi:[1,0,1] neg_lo:[1,0,0] neg_hi:[1,0,0]
	v_pk_fma_f32 v[2:3], v[94:95], v[18:19], v[6:7] op_sel_hi:[1,0,1] neg_lo:[1,0,0] neg_hi:[1,0,0]
	ds_read_b128 v[56:59], v139 offset:6400
	s_waitcnt lgkmcnt(7)
	v_pk_mul_f32 v[8:9], v[118:119], v[126:127] op_sel_hi:[1,0]
	v_pk_mul_f32 v[10:11], v[120:121], v[126:127] op_sel_hi:[1,0]
	v_pk_mul_f32 v[16:17], v[0:1], v[110:111]
	v_pk_mul_f32 v[20:21], v[0:1], v[100:101]
	ds_read_b128 v[74:77], v139 offset:7488
	v_pk_fma_f32 v[16:17], v[2:3], v[112:113], v[16:17]
	v_pk_fma_f32 v[20:21], v[2:3], v[102:103], v[20:21]
	ds_read_b32 v82, v140 offset:6720
	v_add_f32_e32 v18, v16, v17
	v_pk_fma_f32 v[4:5], v[0:1], v[106:107], v[8:9]
	v_add_f32_e32 v14, v20, v21
	v_add_f32_dpp v18, v18, v18 quad_perm:[1,0,3,2] row_mask:0xf bank_mask:0xf bound_ctrl:1
	v_pk_fma_f32 v[6:7], v[2:3], v[108:109], v[10:11]
	v_add_f32_dpp v201, v201, v201 row_half_mirror row_mask:0xf bank_mask:0xa bound_ctrl:1
	v_add_f32_dpp v18, v18, v18 quad_perm:[2,3,0,1] row_mask:0xf bank_mask:0xf bound_ctrl:1
	ds_read_b128 v[66:69], v139 offset:6976
	v_add_f32_dpp v201, v195, v195 row_half_mirror row_mask:0xf bank_mask:0x5 bound_ctrl:1
	v_add_f32_dpp v18, v18, v18 row_half_mirror row_mask:0xf bank_mask:0xf bound_ctrl:1
	ds_read_b128 v[62:65], v139 offset:6720
	v_cndmask_b32_e64 v22, v196, v200, s[36:37]
	v_add_f32_dpp v18, v18, v18 row_ror:8 row_mask:0xf bank_mask:0xf bound_ctrl:1
	ds_read_b128 v[70:73], v139 offset:7232
	v_pk_fma_f32 v[0:1], v[114:115], v[18:19], v[4:5] op_sel_hi:[1,0,1] neg_lo:[1,0,0] neg_hi:[1,0,0]
	v_pk_fma_f32 v[2:3], v[116:117], v[18:19], v[6:7] op_sel_hi:[1,0,1] neg_lo:[1,0,0] neg_hi:[1,0,0]
	ds_read_b128 v[78:81], v139 offset:7744
	s_waitcnt lgkmcnt(7)
	v_pk_mul_f32 v[8:9], v[52:53], v[60:61] op_sel_hi:[1,0]
	v_pk_mul_f32 v[10:11], v[54:55], v[60:61] op_sel_hi:[1,0]
	v_pk_mul_f32 v[16:17], v[0:1], v[44:45]
	v_pk_mul_f32 v[20:21], v[0:1], v[122:123]
	ds_read_b128 v[96:99], v139 offset:8832
	v_pk_fma_f32 v[16:17], v[2:3], v[46:47], v[16:17]
	v_pk_fma_f32 v[20:21], v[2:3], v[124:125], v[20:21]
	ds_read_b32 v104, v140 offset:8064
	v_add_f32_e32 v18, v16, v17
	v_pk_fma_f32 v[4:5], v[0:1], v[40:41], v[8:9]
	v_add_f32_e32 v15, v20, v21
	v_add_f32_dpp v18, v18, v18 quad_perm:[1,0,3,2] row_mask:0xf bank_mask:0xf bound_ctrl:1
	v_pk_fma_f32 v[6:7], v[2:3], v[42:43], v[10:11]
	v_cndmask_b32_e64 v202, v200, v196, s[36:37]
	v_add_f32_dpp v18, v18, v18 quad_perm:[2,3,0,1] row_mask:0xf bank_mask:0xf bound_ctrl:1
	ds_read_b128 v[88:91], v139 offset:8320
	v_add_f32_dpp v200, v202, v22 quad_perm:[2,3,0,1] row_mask:0xf bank_mask:0xf bound_ctrl:1
	v_add_f32_dpp v18, v18, v18 row_half_mirror row_mask:0xf bank_mask:0xf bound_ctrl:1
	ds_read_b128 v[84:87], v139 offset:8064
	v_cndmask_b32_e64 v203, v197, v201, s[36:37]
	v_add_f32_dpp v18, v18, v18 row_ror:8 row_mask:0xf bank_mask:0xf bound_ctrl:1
	ds_read_b128 v[92:95], v139 offset:8576
	v_pk_fma_f32 v[0:1], v[48:49], v[18:19], v[4:5] op_sel_hi:[1,0,1] neg_lo:[1,0,0] neg_hi:[1,0,0]
	v_pk_fma_f32 v[2:3], v[50:51], v[18:19], v[6:7] op_sel_hi:[1,0,1] neg_lo:[1,0,0] neg_hi:[1,0,0]
	ds_read_b128 v[100:103], v139 offset:9088
	s_waitcnt lgkmcnt(7)
	v_pk_mul_f32 v[8:9], v[74:75], v[82:83] op_sel_hi:[1,0]
	v_pk_mul_f32 v[10:11], v[76:77], v[82:83] op_sel_hi:[1,0]
	v_pk_mul_f32 v[16:17], v[0:1], v[66:67]
	v_pk_mul_f32 v[20:21], v[0:1], v[56:57]
	ds_read_b128 v[118:121], v139 offset:10176
	v_pk_fma_f32 v[16:17], v[2:3], v[68:69], v[16:17]
	v_pk_fma_f32 v[20:21], v[2:3], v[58:59], v[20:21]
	ds_read_b32 v126, v140 offset:9408
	v_add_f32_e32 v18, v16, v17
	v_pk_fma_f32 v[4:5], v[0:1], v[62:63], v[8:9]
	v_add_f32_e32 v188, v20, v21
	v_add_f32_dpp v18, v18, v18 quad_perm:[1,0,3,2] row_mask:0xf bank_mask:0xf bound_ctrl:1
	v_pk_fma_f32 v[6:7], v[2:3], v[64:65], v[10:11]
	v_cndmask_b32_e64 v202, v201, v197, s[36:37]
	v_add_f32_dpp v18, v18, v18 quad_perm:[2,3,0,1] row_mask:0xf bank_mask:0xf bound_ctrl:1
	ds_read_b128 v[110:113], v139 offset:9664
	v_add_f32_dpp v201, v202, v203 quad_perm:[2,3,0,1] row_mask:0xf bank_mask:0xf bound_ctrl:1
	v_add_f32_dpp v18, v18, v18 row_half_mirror row_mask:0xf bank_mask:0xf bound_ctrl:1
	ds_read_b128 v[106:109], v139 offset:9408
	v_cndmask_b32_e64 v22, v200, v201, s[38:39]
	v_add_f32_dpp v18, v18, v18 row_ror:8 row_mask:0xf bank_mask:0xf bound_ctrl:1
	ds_read_b128 v[114:117], v139 offset:9920
	v_pk_fma_f32 v[0:1], v[70:71], v[18:19], v[4:5] op_sel_hi:[1,0,1] neg_lo:[1,0,0] neg_hi:[1,0,0]
	v_pk_fma_f32 v[2:3], v[72:73], v[18:19], v[6:7] op_sel_hi:[1,0,1] neg_lo:[1,0,0] neg_hi:[1,0,0]
	ds_read_b128 v[122:125], v139 offset:10432
	s_waitcnt lgkmcnt(7)
	v_pk_mul_f32 v[8:9], v[96:97], v[104:105] op_sel_hi:[1,0]
	v_pk_mul_f32 v[10:11], v[98:99], v[104:105] op_sel_hi:[1,0]
	v_pk_mul_f32 v[16:17], v[0:1], v[88:89]
	v_pk_mul_f32 v[20:21], v[0:1], v[78:79]
	ds_read_b128 v[52:55], v139 offset:11520
	v_pk_fma_f32 v[16:17], v[2:3], v[90:91], v[16:17]
	v_pk_fma_f32 v[20:21], v[2:3], v[80:81], v[20:21]
	ds_read_b32 v60, v140 offset:10752
	v_add_f32_e32 v18, v16, v17
	v_pk_fma_f32 v[4:5], v[0:1], v[84:85], v[8:9]
	v_add_f32_e32 v189, v20, v21
	v_add_f32_dpp v18, v18, v18 quad_perm:[1,0,3,2] row_mask:0xf bank_mask:0xf bound_ctrl:1
	v_pk_fma_f32 v[6:7], v[2:3], v[86:87], v[10:11]
	v_cndmask_b32_e64 v202, v201, v200, s[38:39]
	v_add_f32_dpp v18, v18, v18 quad_perm:[2,3,0,1] row_mask:0xf bank_mask:0xf bound_ctrl:1
	ds_read_b128 v[44:47], v139 offset:11008
	v_add_f32_dpp v23, v202, v22 quad_perm:[1,0,3,2] row_mask:0xf bank_mask:0xf bound_ctrl:1
	v_add_f32_dpp v18, v18, v18 row_half_mirror row_mask:0xf bank_mask:0xf bound_ctrl:1
	ds_read_b128 v[40:43], v139 offset:10752
	s_nop 0
	v_add_f32_dpp v18, v18, v18 row_ror:8 row_mask:0xf bank_mask:0xf bound_ctrl:1
	ds_read_b128 v[48:51], v139 offset:11264
	v_pk_fma_f32 v[0:1], v[92:93], v[18:19], v[4:5] op_sel_hi:[1,0,1] neg_lo:[1,0,0] neg_hi:[1,0,0]
	v_pk_fma_f32 v[2:3], v[94:95], v[18:19], v[6:7] op_sel_hi:[1,0,1] neg_lo:[1,0,0] neg_hi:[1,0,0]
	ds_read_b128 v[56:59], v139 offset:11776
	s_waitcnt lgkmcnt(7)
	v_pk_mul_f32 v[8:9], v[118:119], v[126:127] op_sel_hi:[1,0]
	v_pk_mul_f32 v[10:11], v[120:121], v[126:127] op_sel_hi:[1,0]
	s_cmp_eq_u32 s4, 0
	s_cbranch_scc1 .Lscan_noy0
	global_store_dword v138, v23, s[96:97]
	v_add_u32_e32 v138, s90, v138
.Lscan_noy0:
	v_pk_mul_f32 v[16:17], v[0:1], v[110:111]
	v_pk_mul_f32 v[20:21], v[0:1], v[100:101]
	ds_read_b128 v[74:77], v139 offset:12864
	v_pk_fma_f32 v[16:17], v[2:3], v[112:113], v[16:17]
	v_pk_fma_f32 v[20:21], v[2:3], v[102:103], v[20:21]
	ds_read_b32 v82, v140 offset:12096
	v_add_f32_e32 v18, v16, v17
	v_pk_fma_f32 v[4:5], v[0:1], v[106:107], v[8:9]
	v_add_f32_e32 v190, v20, v21
	v_add_f32_dpp v18, v18, v18 quad_perm:[1,0,3,2] row_mask:0xf bank_mask:0xf bound_ctrl:1
	v_pk_fma_f32 v[6:7], v[2:3], v[108:109], v[10:11]
	s_nop 0
	v_add_f32_dpp v18, v18, v18 quad_perm:[2,3,0,1] row_mask:0xf bank_mask:0xf bound_ctrl:1
	ds_read_b128 v[66:69], v139 offset:12352
	s_nop 0
	v_add_f32_dpp v18, v18, v18 row_half_mirror row_mask:0xf bank_mask:0xf bound_ctrl:1
	ds_read_b128 v[62:65], v139 offset:12096
	s_nop 0
	v_add_f32_dpp v18, v18, v18 row_ror:8 row_mask:0xf bank_mask:0xf bound_ctrl:1
	ds_read_b128 v[70:73], v139 offset:12608
	v_pk_fma_f32 v[0:1], v[114:115], v[18:19], v[4:5] op_sel_hi:[1,0,1] neg_lo:[1,0,0] neg_hi:[1,0,0]
	v_pk_fma_f32 v[2:3], v[116:117], v[18:19], v[6:7] op_sel_hi:[1,0,1] neg_lo:[1,0,0] neg_hi:[1,0,0]
	ds_read_b128 v[78:81], v139 offset:13120
	s_waitcnt lgkmcnt(7)
	v_pk_mul_f32 v[8:9], v[52:53], v[60:61] op_sel_hi:[1,0]
	v_pk_mul_f32 v[10:11], v[54:55], v[60:61] op_sel_hi:[1,0]
	v_pk_mul_f32 v[16:17], v[0:1], v[44:45]
	v_pk_mul_f32 v[20:21], v[0:1], v[122:123]
	ds_read_b128 v[96:99], v139 offset:14208
	v_pk_fma_f32 v[16:17], v[2:3], v[46:47], v[16:17]
	v_pk_fma_f32 v[20:21], v[2:3], v[124:125], v[20:21]
	ds_read_b32 v104, v140 offset:13440
	v_add_f32_e32 v18, v16, v17
	v_pk_fma_f32 v[4:5], v[0:1], v[40:41], v[8:9]
	v_add_f32_e32 v191, v20, v21
	v_add_f32_dpp v18, v18, v18 quad_perm:[1,0,3,2] row_mask:0xf bank_mask:0xf bound_ctrl:1
	v_pk_fma_f32 v[6:7], v[2:3], v[42:43], v[10:11]
	s_nop 0
	v_add_f32_dpp v18, v18, v18 quad_perm:[2,3,0,1] row_mask:0xf bank_mask:0xf bound_ctrl:1
	ds_read_b128 v[88:91], v139 offset:13696
	s_nop 0
	v_add_f32_dpp v18, v18, v18 row_half_mirror row_mask:0xf bank_mask:0xf bound_ctrl:1
	ds_read_b128 v[84:87], v139 offset:13440
	s_nop 0
	v_add_f32_dpp v18, v18, v18 row_ror:8 row_mask:0xf bank_mask:0xf bound_ctrl:1
	ds_read_b128 v[92:95], v139 offset:13952
	v_pk_fma_f32 v[0:1], v[48:49], v[18:19], v[4:5] op_sel_hi:[1,0,1] neg_lo:[1,0,0] neg_hi:[1,0,0]
	v_pk_fma_f32 v[2:3], v[50:51], v[18:19], v[6:7] op_sel_hi:[1,0,1] neg_lo:[1,0,0] neg_hi:[1,0,0]
	ds_read_b128 v[100:103], v139 offset:14464
	s_waitcnt lgkmcnt(7)
	v_pk_mul_f32 v[8:9], v[74:75], v[82:83] op_sel_hi:[1,0]
	v_pk_mul_f32 v[10:11], v[76:77], v[82:83] op_sel_hi:[1,0]
	v_pk_mul_f32 v[16:17], v[0:1], v[66:67]
	v_pk_mul_f32 v[20:21], v[0:1], v[56:57]
	ds_read_b128 v[118:121], v139 offset:15552
	v_pk_fma_f32 v[16:17], v[2:3], v[68:69], v[16:17]
	v_pk_fma_f32 v[20:21], v[2:3], v[58:59], v[20:21]
	ds_read_b32 v126, v140 offset:14784
	v_add_f32_e32 v18, v16, v17
	v_pk_fma_f32 v[4:5], v[0:1], v[62:63], v[8:9]
	v_add_f32_e32 v192, v20, v21
	v_add_f32_dpp v18, v18, v18 quad_perm:[1,0,3,2] row_mask:0xf bank_mask:0xf bound_ctrl:1
	v_pk_fma_f32 v[6:7], v[2:3], v[64:65], v[10:11]
	s_nop 0
	v_add_f32_dpp v18, v18, v18 quad_perm:[2,3,0,1] row_mask:0xf bank_mask:0xf bound_ctrl:1
	ds_read_b128 v[110:113], v139 offset:15040
	v_add_f32_dpp v192, v192, v192 row_ror:8 row_mask:0xf bank_mask:0xc bound_ctrl:1
	v_add_f32_dpp v18, v18, v18 row_half_mirror row_mask:0xf bank_mask:0xf bound_ctrl:1
	ds_read_b128 v[106:109], v139 offset:14784
	v_add_f32_dpp v192, v12, v12 row_ror:8 row_mask:0xf bank_mask:0x3 bound_ctrl:1
	v_add_f32_dpp v18, v18, v18 row_ror:8 row_mask:0xf bank_mask:0xf bound_ctrl:1
	ds_read_b128 v[114:117], v139 offset:15296
	v_pk_fma_f32 v[0:1], v[70:71], v[18:19], v[4:5] op_sel_hi:[1,0,1] neg_lo:[1,0,0] neg_hi:[1,0,0]
	v_pk_fma_f32 v[2:3], v[72:73], v[18:19], v[6:7] op_sel_hi:[1,0,1] neg_lo:[1,0,0] neg_hi:[1,0,0]
	ds_read_b128 v[122:125], v139 offset:15808
	s_waitcnt lgkmcnt(7)
	v_pk_mul_f32 v[8:9], v[96:97], v[104:105] op_sel_hi:[1,0]
	v_pk_mul_f32 v[10:11], v[98:99], v[104:105] op_sel_hi:[1,0]
	v_pk_mul_f32 v[16:17], v[0:1], v[88:89]
	v_pk_mul_f32 v[20:21], v[0:1], v[78:79]
	ds_read_b128 v[52:55], v139 offset:16896
	v_pk_fma_f32 v[16:17], v[2:3], v[90:91], v[16:17]
	v_pk_fma_f32 v[20:21], v[2:3], v[80:81], v[20:21]
	ds_read_b32 v60, v140 offset:16128
	v_add_f32_e32 v18, v16, v17
	v_pk_fma_f32 v[4:5], v[0:1], v[84:85], v[8:9]
	v_add_f32_e32 v193, v20, v21
	v_add_f32_dpp v18, v18, v18 quad_perm:[1,0,3,2] row_mask:0xf bank_mask:0xf bound_ctrl:1
	v_pk_fma_f32 v[6:7], v[2:3], v[86:87], v[10:11]
	s_nop 0
	v_add_f32_dpp v18, v18, v18 quad_perm:[2,3,0,1] row_mask:0xf bank_mask:0xf bound_ctrl:1
	ds_read_b128 v[44:47], v139 offset:16384
	v_add_f32_dpp v193, v193, v193 row_ror:8 row_mask:0xf bank_mask:0xc bound_ctrl:1
	v_add_f32_dpp v18, v18, v18 row_half_mirror row_mask:0xf bank_mask:0xf bound_ctrl:1
	ds_read_b128 v[40:43], v139 offset:16128
	v_add_f32_dpp v193, v13, v13 row_ror:8 row_mask:0xf bank_mask:0x3 bound_ctrl:1
	v_add_f32_dpp v18, v18, v18 row_ror:8 row_mask:0xf bank_mask:0xf bound_ctrl:1
	ds_read_b128 v[48:51], v139 offset:16640
	v_pk_fma_f32 v[0:1], v[92:93], v[18:19], v[4:5] op_sel_hi:[1,0,1] neg_lo:[1,0,0] neg_hi:[1,0,0]
	v_pk_fma_f32 v[2:3], v[94:95], v[18:19], v[6:7] op_sel_hi:[1,0,1] neg_lo:[1,0,0] neg_hi:[1,0,0]
	ds_read_b128 v[56:59], v139 offset:17152
	s_waitcnt lgkmcnt(7)
	v_pk_mul_f32 v[8:9], v[118:119], v[126:127] op_sel_hi:[1,0]
	v_pk_mul_f32 v[10:11], v[120:121], v[126:127] op_sel_hi:[1,0]
	s_add_i32 s0, s4, 2
	s_cmp_lt_u32 s0, s5
	s_cbranch_scc1 .Lscan_w6_0
	s_waitcnt vmcnt(0)
	s_branch .Lscan_wd_0

.Lscan_wd_0:
	ds_write_b128 v143, v[146:149]
	ds_write_b128 v143, v[150:153] offset:256
	ds_write_b128 v143, v[154:157] offset:512
	ds_write_b128 v143, v[158:161] offset:768
	ds_write_b128 v143, v[162:165] offset:1024
	ds_write_b32 v35, v166
	v_pk_mul_f32 v[16:17], v[0:1], v[110:111]
	v_pk_mul_f32 v[20:21], v[0:1], v[100:101]
	ds_read_b128 v[74:77], v139 offset:18240
	v_pk_fma_f32 v[16:17], v[2:3], v[112:113], v[16:17]
	v_pk_fma_f32 v[20:21], v[2:3], v[102:103], v[20:21]
	ds_read_b32 v82, v140 offset:17472
	v_add_f32_e32 v18, v16, v17
	v_pk_fma_f32 v[4:5], v[0:1], v[106:107], v[8:9]
	v_add_f32_e32 v194, v20, v21
	v_add_f32_dpp v18, v18, v18 quad_perm:[1,0,3,2] row_mask:0xf bank_mask:0xf bound_ctrl:1
	v_pk_fma_f32 v[6:7], v[2:3], v[108:109], v[10:11]
	s_nop 0
	v_add_f32_dpp v18, v18, v18 quad_perm:[2,3,0,1] row_mask:0xf bank_mask:0xf bound_ctrl:1
	ds_read_b128 v[66:69], v139 offset:17728
	v_add_f32_dpp v194, v194, v194 row_ror:8 row_mask:0xf bank_mask:0xc bound_ctrl:1
	v_add_f32_dpp v18, v18, v18 row_half_mirror row_mask:0xf bank_mask:0xf bound_ctrl:1
	ds_read_b128 v[62:65], v139 offset:17472
	v_add_f32_dpp v194, v14, v14 row_ror:8 row_mask:0xf bank_mask:0x3 bound_ctrl:1
	v_add_f32_dpp v18, v18, v18 row_ror:8 row_mask:0xf bank_mask:0xf bound_ctrl:1
	ds_read_b128 v[70:73], v139 offset:17984
	v_pk_fma_f32 v[0:1], v[114:115], v[18:19], v[4:5] op_sel_hi:[1,0,1] neg_lo:[1,0,0] neg_hi:[1,0,0]
	v_pk_fma_f32 v[2:3], v[116:117], v[18:19], v[6:7] op_sel_hi:[1,0,1] neg_lo:[1,0,0] neg_hi:[1,0,0]
	ds_read_b128 v[78:81], v139 offset:18496
	s_waitcnt lgkmcnt(7)
	v_pk_mul_f32 v[8:9], v[52:53], v[60:61] op_sel_hi:[1,0]
	v_pk_mul_f32 v[10:11], v[54:55], v[60:61] op_sel_hi:[1,0]
	v_pk_mul_f32 v[16:17], v[0:1], v[44:45]
	v_pk_mul_f32 v[20:21], v[0:1], v[122:123]
	ds_read_b128 v[96:99], v139 offset:19584
	v_pk_fma_f32 v[16:17], v[2:3], v[46:47], v[16:17]
	v_pk_fma_f32 v[20:21], v[2:3], v[124:125], v[20:21]
	ds_read_b32 v104, v140 offset:18816
	v_add_f32_e32 v18, v16, v17
	v_pk_fma_f32 v[4:5], v[0:1], v[40:41], v[8:9]
	v_add_f32_e32 v195, v20, v21
	v_add_f32_dpp v18, v18, v18 quad_perm:[1,0,3,2] row_mask:0xf bank_mask:0xf bound_ctrl:1
	v_pk_fma_f32 v[6:7], v[2:3], v[42:43], v[10:11]
	s_nop 0
	v_add_f32_dpp v18, v18, v18 quad_perm:[2,3,0,1] row_mask:0xf bank_mask:0xf bound_ctrl:1
	ds_read_b128 v[88:91], v139 offset:19072
	v_add_f32_dpp v195, v195, v195 row_ror:8 row_mask:0xf bank_mask:0xc bound_ctrl:1
	v_add_f32_dpp v18, v18, v18 row_half_mirror row_mask:0xf bank_mask:0xf bound_ctrl:1
	ds_read_b128 v[84:87], v139 offset:18816
	v_add_f32_dpp v195, v15, v15 row_ror:8 row_mask:0xf bank_mask:0x3 bound_ctrl:1
	v_add_f32_dpp v18, v18, v18 row_ror:8 row_mask:0xf bank_mask:0xf bound_ctrl:1
	ds_read_b128 v[92:95], v139 offset:19328
	v_pk_fma_f32 v[0:1], v[48:49], v[18:19], v[4:5] op_sel_hi:[1,0,1] neg_lo:[1,0,0] neg_hi:[1,0,0]
	v_pk_fma_f32 v[2:3], v[50:51], v[18:19], v[6:7] op_sel_hi:[1,0,1] neg_lo:[1,0,0] neg_hi:[1,0,0]
	ds_read_b128 v[100:103], v139 offset:19840
	s_waitcnt lgkmcnt(7)
	s_barrier
	s_add_i32 s0, s4, 3
	s_cmp_lt_u32 s0, s5
	s_cbranch_scc0 .Lscan_nold0
	s_mul_i32 s92, s0, s90
	v_add_u32_e32 v132, s92, v28
	v_add_u32_e32 v133, s92, v29
	v_add_u32_e32 v134, s92, v30
	v_add_u32_e32 v135, s92, v31
	v_add_u32_e32 v136, s92, v32
	v_add_u32_e32 v137, s92, v33
	global_load_dwordx4 v[146:149], v132, s[96:97]
	global_load_dwordx4 v[150:153], v133, s[96:97]
	global_load_dwordx4 v[154:157], v134, s[96:97]
	global_load_dwordx4 v[158:161], v135, s[96:97]
	global_load_dwordx4 v[162:165], v136, s[96:97]
	global_load_dword v166, v137, s[96:97]
.Lscan_nold0:
	v_pk_mul_f32 v[8:9], v[74:75], v[82:83] op_sel_hi:[1,0]
	v_pk_mul_f32 v[10:11], v[76:77], v[82:83] op_sel_hi:[1,0]
	v_pk_mul_f32 v[16:17], v[0:1], v[66:67]
	v_pk_mul_f32 v[20:21], v[0:1], v[56:57]
	ds_read_b128 v[118:121], v139 offset:20928
	v_pk_fma_f32 v[16:17], v[2:3], v[68:69], v[16:17]
	v_pk_fma_f32 v[20:21], v[2:3], v[58:59], v[20:21]
	ds_read_b32 v126, v140 offset:20160
	v_add_f32_e32 v18, v16, v17
	v_pk_fma_f32 v[4:5], v[0:1], v[62:63], v[8:9]
	v_add_f32_e32 v196, v20, v21
	v_add_f32_dpp v18, v18, v18 quad_perm:[1,0,3,2] row_mask:0xf bank_mask:0xf bound_ctrl:1
	v_pk_fma_f32 v[6:7], v[2:3], v[64:65], v[10:11]
	s_nop 0
	v_add_f32_dpp v18, v18, v18 quad_perm:[2,3,0,1] row_mask:0xf bank_mask:0xf bound_ctrl:1
	ds_read_b128 v[110:113], v139 offset:20416
	v_add_f32_dpp v196, v196, v196 row_ror:8 row_mask:0xf bank_mask:0xc bound_ctrl:1
	v_add_f32_dpp v18, v18, v18 row_half_mirror row_mask:0xf bank_mask:0xf bound_ctrl:1
	ds_read_b128 v[106:109], v139 offset:20160
	v_add_f32_dpp v196, v188, v188 row_ror:8 row_mask:0xf bank_mask:0x3 bound_ctrl:1
	v_add_f32_dpp v18, v18, v18 row_ror:8 row_mask:0xf bank_mask:0xf bound_ctrl:1
	ds_read_b128 v[114:117], v139 offset:20672
	v_pk_fma_f32 v[0:1], v[70:71], v[18:19], v[4:5] op_sel_hi:[1,0,1] neg_lo:[1,0,0] neg_hi:[1,0,0]
	v_pk_fma_f32 v[2:3], v[72:73], v[18:19], v[6:7] op_sel_hi:[1,0,1] neg_lo:[1,0,0] neg_hi:[1,0,0]
	ds_read_b128 v[122:125], v139 offset:21184
	s_waitcnt lgkmcnt(7)
	v_pk_mul_f32 v[8:9], v[96:97], v[104:105] op_sel_hi:[1,0]
	v_pk_mul_f32 v[10:11], v[98:99], v[104:105] op_sel_hi:[1,0]
	v_pk_mul_f32 v[16:17], v[0:1], v[88:89]
	v_pk_mul_f32 v[20:21], v[0:1], v[78:79]
	ds_read_b128 v[52:55], v141 offset:768
	v_pk_fma_f32 v[16:17], v[2:3], v[90:91], v[16:17]
	v_pk_fma_f32 v[20:21], v[2:3], v[80:81], v[20:21]
	ds_read_b32 v60, v142 offset:0
	v_add_f32_e32 v18, v16, v17
	v_pk_fma_f32 v[4:5], v[0:1], v[84:85], v[8:9]
	v_add_f32_e32 v197, v20, v21
	v_add_f32_dpp v18, v18, v18 quad_perm:[1,0,3,2] row_mask:0xf bank_mask:0xf bound_ctrl:1
	v_pk_fma_f32 v[6:7], v[2:3], v[86:87], v[10:11]
	s_nop 0
	v_add_f32_dpp v18, v18, v18 quad_perm:[2,3,0,1] row_mask:0xf bank_mask:0xf bound_ctrl:1
	ds_read_b128 v[44:47], v141 offset:256
	v_add_f32_dpp v197, v197, v197 row_ror:8 row_mask:0xf bank_mask:0xc bound_ctrl:1
	v_add_f32_dpp v18, v18, v18 row_half_mirror row_mask:0xf bank_mask:0xf bound_ctrl:1
	ds_read_b128 v[40:43], v141 offset:0
	v_add_f32_dpp v197, v189, v189 row_ror:8 row_mask:0xf bank_mask:0x3 bound_ctrl:1
	v_add_f32_dpp v18, v18, v18 row_ror:8 row_mask:0xf bank_mask:0xf bound_ctrl:1
	ds_read_b128 v[48:51], v141 offset:512
	v_pk_fma_f32 v[0:1], v[92:93], v[18:19], v[4:5] op_sel_hi:[1,0,1] neg_lo:[1,0,0] neg_hi:[1,0,0]
	v_pk_fma_f32 v[2:3], v[94:95], v[18:19], v[6:7] op_sel_hi:[1,0,1] neg_lo:[1,0,0] neg_hi:[1,0,0]
	ds_read_b128 v[56:59], v141 offset:1024
	s_waitcnt lgkmcnt(7)
	v_pk_mul_f32 v[8:9], v[118:119], v[126:127] op_sel_hi:[1,0]
	v_pk_mul_f32 v[10:11], v[120:121], v[126:127] op_sel_hi:[1,0]
	v_pk_mul_f32 v[16:17], v[0:1], v[110:111]
	v_pk_mul_f32 v[20:21], v[0:1], v[100:101]
	ds_read_b128 v[74:77], v141 offset:2112
	v_pk_fma_f32 v[16:17], v[2:3], v[112:113], v[16:17]
	v_pk_fma_f32 v[20:21], v[2:3], v[102:103], v[20:21]
	ds_read_b32 v82, v142 offset:1344
	v_add_f32_e32 v18, v16, v17
	v_pk_fma_f32 v[4:5], v[0:1], v[106:107], v[8:9]
	v_add_f32_e32 v200, v20, v21
	v_add_f32_dpp v18, v18, v18 quad_perm:[1,0,3,2] row_mask:0xf bank_mask:0xf bound_ctrl:1
	v_pk_fma_f32 v[6:7], v[2:3], v[108:109], v[10:11]
	s_nop 0
	v_add_f32_dpp v18, v18, v18 quad_perm:[2,3,0,1] row_mask:0xf bank_mask:0xf bound_ctrl:1
	ds_read_b128 v[66:69], v141 offset:1600
	v_add_f32_dpp v200, v200, v200 row_ror:8 row_mask:0xf bank_mask:0xc bound_ctrl:1
	v_add_f32_dpp v18, v18, v18 row_half_mirror row_mask:0xf bank_mask:0xf bound_ctrl:1
	ds_read_b128 v[62:65], v141 offset:1344
	v_add_f32_dpp v200, v190, v190 row_ror:8 row_mask:0xf bank_mask:0x3 bound_ctrl:1
	v_add_f32_dpp v18, v18, v18 row_ror:8 row_mask:0xf bank_mask:0xf bound_ctrl:1
	ds_read_b128 v[70:73], v141 offset:1856
	v_pk_fma_f32 v[0:1], v[114:115], v[18:19], v[4:5] op_sel_hi:[1,0,1] neg_lo:[1,0,0] neg_hi:[1,0,0]
	v_pk_fma_f32 v[2:3], v[116:117], v[18:19], v[6:7] op_sel_hi:[1,0,1] neg_lo:[1,0,0] neg_hi:[1,0,0]
	ds_read_b128 v[78:81], v141 offset:2368
	s_waitcnt lgkmcnt(7)
	v_pk_mul_f32 v[8:9], v[52:53], v[60:61] op_sel_hi:[1,0]
	v_pk_mul_f32 v[10:11], v[54:55], v[60:61] op_sel_hi:[1,0]
	s_add_i32 s4, s4, 1
	s_mov_b32 s0, s6
	s_mov_b32 s6, s7
	s_mov_b32 s7, s25
	s_mov_b32 s25, s0
	v_mov_b32_e32 v139, v141
	v_mov_b32_e32 v140, v142
	v_add_u32_e32 v141, s7, v24
	v_add_u32_e32 v142, s7, v25
	v_add_u32_e32 v143, s7, v26
	v_add_u32_e32 v35, s7, v27
	v_pk_mul_f32 v[16:17], v[0:1], v[44:45]
	v_pk_mul_f32 v[20:21], v[0:1], v[122:123]
	ds_read_b128 v[96:99], v139 offset:3456
	v_pk_fma_f32 v[16:17], v[2:3], v[46:47], v[16:17]
	v_pk_fma_f32 v[20:21], v[2:3], v[124:125], v[20:21]
	ds_read_b32 v104, v140 offset:2688
	v_add_f32_e32 v18, v16, v17
	v_pk_fma_f32 v[4:5], v[0:1], v[40:41], v[8:9]
	v_add_f32_e32 v201, v20, v21
	v_add_f32_dpp v18, v18, v18 quad_perm:[1,0,3,2] row_mask:0xf bank_mask:0xf bound_ctrl:1
	v_pk_fma_f32 v[6:7], v[2:3], v[42:43], v[10:11]
	s_nop 0
	v_add_f32_dpp v18, v18, v18 quad_perm:[2,3,0,1] row_mask:0xf bank_mask:0xf bound_ctrl:1
	ds_read_b128 v[88:91], v139 offset:2944
	v_add_f32_dpp v201, v201, v201 row_ror:8 row_mask:0xf bank_mask:0xc bound_ctrl:1
	v_add_f32_dpp v18, v18, v18 row_half_mirror row_mask:0xf bank_mask:0xf bound_ctrl:1
	ds_read_b128 v[84:87], v139 offset:2688
	v_add_f32_dpp v201, v191, v191 row_ror:8 row_mask:0xf bank_mask:0x3 bound_ctrl:1
	v_add_f32_dpp v18, v18, v18 row_ror:8 row_mask:0xf bank_mask:0xf bound_ctrl:1
	ds_read_b128 v[92:95], v139 offset:3200
	v_pk_fma_f32 v[0:1], v[48:49], v[18:19], v[4:5] op_sel_hi:[1,0,1] neg_lo:[1,0,0] neg_hi:[1,0,0]
	v_pk_fma_f32 v[2:3], v[50:51], v[18:19], v[6:7] op_sel_hi:[1,0,1] neg_lo:[1,0,0] neg_hi:[1,0,0]
	ds_read_b128 v[100:103], v139 offset:3712
	s_waitcnt lgkmcnt(7)
	v_pk_mul_f32 v[8:9], v[74:75], v[82:83] op_sel_hi:[1,0]
	v_pk_mul_f32 v[10:11], v[76:77], v[82:83] op_sel_hi:[1,0]
	v_pk_mul_f32 v[16:17], v[0:1], v[66:67]
	v_pk_mul_f32 v[20:21], v[0:1], v[56:57]
	ds_read_b128 v[118:121], v139 offset:4800
	v_pk_fma_f32 v[16:17], v[2:3], v[68:69], v[16:17]
	v_pk_fma_f32 v[20:21], v[2:3], v[58:59], v[20:21]
	ds_read_b32 v126, v140 offset:4032
	v_add_f32_e32 v18, v16, v17
	v_pk_fma_f32 v[4:5], v[0:1], v[62:63], v[8:9]
	v_add_f32_e32 v12, v20, v21
	v_add_f32_dpp v18, v18, v18 quad_perm:[1,0,3,2] row_mask:0xf bank_mask:0xf bound_ctrl:1
	v_pk_fma_f32 v[6:7], v[2:3], v[64:65], v[10:11]
	v_add_f32_dpp v196, v196, v196 row_half_mirror row_mask:0xf bank_mask:0xa bound_ctrl:1
	v_add_f32_dpp v18, v18, v18 quad_perm:[2,3,0,1] row_mask:0xf bank_mask:0xf bound_ctrl:1
	ds_read_b128 v[110:113], v139 offset:4288
	v_add_f32_dpp v196, v192, v192 row_half_mirror row_mask:0xf bank_mask:0x5 bound_ctrl:1
	v_add_f32_dpp v18, v18, v18 row_half_mirror row_mask:0xf bank_mask:0xf bound_ctrl:1
	ds_read_b128 v[106:109], v139 offset:4032
	v_add_f32_dpp v197, v197, v197 row_half_mirror row_mask:0xf bank_mask:0xa bound_ctrl:1
	v_add_f32_dpp v18, v18, v18 row_ror:8 row_mask:0xf bank_mask:0xf bound_ctrl:1
	ds_read_b128 v[114:117], v139 offset:4544
	v_pk_fma_f32 v[0:1], v[70:71], v[18:19], v[4:5] op_sel_hi:[1,0,1] neg_lo:[1,0,0] neg_hi:[1,0,0]
	v_pk_fma_f32 v[2:3], v[72:73], v[18:19], v[6:7] op_sel_hi:[1,0,1] neg_lo:[1,0,0] neg_hi:[1,0,0]
	ds_read_b128 v[122:125], v139 offset:5056
	s_waitcnt lgkmcnt(7)
	v_pk_mul_f32 v[8:9], v[96:97], v[104:105] op_sel_hi:[1,0]
	v_pk_mul_f32 v[10:11], v[98:99], v[104:105] op_sel_hi:[1,0]
	v_pk_mul_f32 v[16:17], v[0:1], v[88:89]
	v_pk_mul_f32 v[20:21], v[0:1], v[78:79]
	ds_read_b128 v[52:55], v139 offset:6144
	v_pk_fma_f32 v[16:17], v[2:3], v[90:91], v[16:17]
	v_pk_fma_f32 v[20:21], v[2:3], v[80:81], v[20:21]
	ds_read_b32 v60, v140 offset:5376
	v_add_f32_e32 v18, v16, v17
	v_pk_fma_f32 v[4:5], v[0:1], v[84:85], v[8:9]
	v_add_f32_e32 v13, v20, v21
	v_add_f32_dpp v18, v18, v18 quad_perm:[1,0,3,2] row_mask:0xf bank_mask:0xf bound_ctrl:1
	v_pk_fma_f32 v[6:7], v[2:3], v[86:87], v[10:11]
	v_add_f32_dpp v197, v193, v193 row_half_mirror row_mask:0xf bank_mask:0x5 bound_ctrl:1
	v_add_f32_dpp v18, v18, v18 quad_perm:[2,3,0,1] row_mask:0xf bank_mask:0xf bound_ctrl:1
	ds_read_b128 v[44:47], v139 offset:5632
	v_add_f32_dpp v200, v200, v200 row_half_mirror row_mask:0xf bank_mask:0xa bound_ctrl:1
	v_add_f32_dpp v18, v18, v18 row_half_mirror row_mask:0xf bank_mask:0xf bound_ctrl:1
	ds_read_b128 v[40:43], v139 offset:5376
	v_add_f32_dpp v200, v194, v194 row_half_mirror row_mask:0xf bank_mask:0x5 bound_ctrl:1
	v_add_f32_dpp v18, v18, v18 row_ror:8 row_mask:0xf bank_mask:0xf bound_ctrl:1
	ds_read_b128 v[48:51], v139 offset:5888
	v_pk_fma_f32 v[0:1], v[92:93], v[18:19], v[4:5] op_sel_hi:[1,0,1] neg_lo:[1,0,0] neg_hi:[1,0,0]
	v_pk_fma_f32 v[2:3], v[94:95], v[18:19], v[6:7] op_sel_hi:[1,0,1] neg_lo:[1,0,0] neg_hi:[1,0,0]
	ds_read_b128 v[56:59], v139 offset:6400
	s_waitcnt lgkmcnt(7)
	v_pk_mul_f32 v[8:9], v[118:119], v[126:127] op_sel_hi:[1,0]
	v_pk_mul_f32 v[10:11], v[120:121], v[126:127] op_sel_hi:[1,0]
	v_pk_mul_f32 v[16:17], v[0:1], v[110:111]
	v_pk_mul_f32 v[20:21], v[0:1], v[100:101]
	ds_read_b128 v[74:77], v139 offset:7488
	v_pk_fma_f32 v[16:17], v[2:3], v[112:113], v[16:17]
	v_pk_fma_f32 v[20:21], v[2:3], v[102:103], v[20:21]
	ds_read_b32 v82, v140 offset:6720
	v_add_f32_e32 v18, v16, v17
	v_pk_fma_f32 v[4:5], v[0:1], v[106:107], v[8:9]
	v_add_f32_e32 v14, v20, v21
	v_add_f32_dpp v18, v18, v18 quad_perm:[1,0,3,2] row_mask:0xf bank_mask:0xf bound_ctrl:1
	v_pk_fma_f32 v[6:7], v[2:3], v[108:109], v[10:11]
	v_add_f32_dpp v201, v201, v201 row_half_mirror row_mask:0xf bank_mask:0xa bound_ctrl:1
	v_add_f32_dpp v18, v18, v18 quad_perm:[2,3,0,1] row_mask:0xf bank_mask:0xf bound_ctrl:1
	ds_read_b128 v[66:69], v139 offset:6976
	v_add_f32_dpp v201, v195, v195 row_half_mirror row_mask:0xf bank_mask:0x5 bound_ctrl:1
	v_add_f32_dpp v18, v18, v18 row_half_mirror row_mask:0xf bank_mask:0xf bound_ctrl:1
	ds_read_b128 v[62:65], v139 offset:6720
	v_cndmask_b32_e64 v22, v196, v200, s[36:37]
	v_add_f32_dpp v18, v18, v18 row_ror:8 row_mask:0xf bank_mask:0xf bound_ctrl:1
	ds_read_b128 v[70:73], v139 offset:7232
	v_pk_fma_f32 v[0:1], v[114:115], v[18:19], v[4:5] op_sel_hi:[1,0,1] neg_lo:[1,0,0] neg_hi:[1,0,0]
	v_pk_fma_f32 v[2:3], v[116:117], v[18:19], v[6:7] op_sel_hi:[1,0,1] neg_lo:[1,0,0] neg_hi:[1,0,0]
	ds_read_b128 v[78:81], v139 offset:7744
	s_waitcnt lgkmcnt(7)
	v_pk_mul_f32 v[8:9], v[52:53], v[60:61] op_sel_hi:[1,0]
	v_pk_mul_f32 v[10:11], v[54:55], v[60:61] op_sel_hi:[1,0]
	v_pk_mul_f32 v[16:17], v[0:1], v[44:45]
	v_pk_mul_f32 v[20:21], v[0:1], v[122:123]
	ds_read_b128 v[96:99], v139 offset:8832
	v_pk_fma_f32 v[16:17], v[2:3], v[46:47], v[16:17]
	v_pk_fma_f32 v[20:21], v[2:3], v[124:125], v[20:21]
	ds_read_b32 v104, v140 offset:8064
	v_add_f32_e32 v18, v16, v17
	v_pk_fma_f32 v[4:5], v[0:1], v[40:41], v[8:9]
	v_add_f32_e32 v15, v20, v21
	v_add_f32_dpp v18, v18, v18 quad_perm:[1,0,3,2] row_mask:0xf bank_mask:0xf bound_ctrl:1
	v_pk_fma_f32 v[6:7], v[2:3], v[42:43], v[10:11]
	v_cndmask_b32_e64 v202, v200, v196, s[36:37]
	v_add_f32_dpp v18, v18, v18 quad_perm:[2,3,0,1] row_mask:0xf bank_mask:0xf bound_ctrl:1
	ds_read_b128 v[88:91], v139 offset:8320
	v_add_f32_dpp v200, v202, v22 quad_perm:[2,3,0,1] row_mask:0xf bank_mask:0xf bound_ctrl:1
	v_add_f32_dpp v18, v18, v18 row_half_mirror row_mask:0xf bank_mask:0xf bound_ctrl:1
	ds_read_b128 v[84:87], v139 offset:8064
	v_cndmask_b32_e64 v203, v197, v201, s[36:37]
	v_add_f32_dpp v18, v18, v18 row_ror:8 row_mask:0xf bank_mask:0xf bound_ctrl:1
	ds_read_b128 v[92:95], v139 offset:8576
	v_pk_fma_f32 v[0:1], v[48:49], v[18:19], v[4:5] op_sel_hi:[1,0,1] neg_lo:[1,0,0] neg_hi:[1,0,0]
	v_pk_fma_f32 v[2:3], v[50:51], v[18:19], v[6:7] op_sel_hi:[1,0,1] neg_lo:[1,0,0] neg_hi:[1,0,0]
	ds_read_b128 v[100:103], v139 offset:9088
	s_waitcnt lgkmcnt(7)
	v_pk_mul_f32 v[8:9], v[74:75], v[82:83] op_sel_hi:[1,0]
	v_pk_mul_f32 v[10:11], v[76:77], v[82:83] op_sel_hi:[1,0]
	v_pk_mul_f32 v[16:17], v[0:1], v[66:67]
	v_pk_mul_f32 v[20:21], v[0:1], v[56:57]
	ds_read_b128 v[118:121], v139 offset:10176
	v_pk_fma_f32 v[16:17], v[2:3], v[68:69], v[16:17]
	v_pk_fma_f32 v[20:21], v[2:3], v[58:59], v[20:21]
	ds_read_b32 v126, v140 offset:9408
	v_add_f32_e32 v18, v16, v17
	v_pk_fma_f32 v[4:5], v[0:1], v[62:63], v[8:9]
	v_add_f32_e32 v188, v20, v21
	v_add_f32_dpp v18, v18, v18 quad_perm:[1,0,3,2] row_mask:0xf bank_mask:0xf bound_ctrl:1
	v_pk_fma_f32 v[6:7], v[2:3], v[64:65], v[10:11]
	v_cndmask_b32_e64 v202, v201, v197, s[36:37]
	v_add_f32_dpp v18, v18, v18 quad_perm:[2,3,0,1] row_mask:0xf bank_mask:0xf bound_ctrl:1
	ds_read_b128 v[110:113], v139 offset:9664
	v_add_f32_dpp v201, v202, v203 quad_perm:[2,3,0,1] row_mask:0xf bank_mask:0xf bound_ctrl:1
	v_add_f32_dpp v18, v18, v18 row_half_mirror row_mask:0xf bank_mask:0xf bound_ctrl:1
	ds_read_b128 v[106:109], v139 offset:9408
	v_cndmask_b32_e64 v22, v200, v201, s[38:39]
	v_add_f32_dpp v18, v18, v18 row_ror:8 row_mask:0xf bank_mask:0xf bound_ctrl:1
	ds_read_b128 v[114:117], v139 offset:9920
	v_pk_fma_f32 v[0:1], v[70:71], v[18:19], v[4:5] op_sel_hi:[1,0,1] neg_lo:[1,0,0] neg_hi:[1,0,0]
	v_pk_fma_f32 v[2:3], v[72:73], v[18:19], v[6:7] op_sel_hi:[1,0,1] neg_lo:[1,0,0] neg_hi:[1,0,0]
	ds_read_b128 v[122:125], v139 offset:10432
	s_waitcnt lgkmcnt(7)
	v_pk_mul_f32 v[8:9], v[96:97], v[104:105] op_sel_hi:[1,0]
	v_pk_mul_f32 v[10:11], v[98:99], v[104:105] op_sel_hi:[1,0]
	v_pk_mul_f32 v[16:17], v[0:1], v[88:89]
	v_pk_mul_f32 v[20:21], v[0:1], v[78:79]
	ds_read_b128 v[52:55], v139 offset:11520
	v_pk_fma_f32 v[16:17], v[2:3], v[90:91], v[16:17]
	v_pk_fma_f32 v[20:21], v[2:3], v[80:81], v[20:21]
	ds_read_b32 v60, v140 offset:10752
	v_add_f32_e32 v18, v16, v17
	v_pk_fma_f32 v[4:5], v[0:1], v[84:85], v[8:9]
	v_add_f32_e32 v189, v20, v21
	v_add_f32_dpp v18, v18, v18 quad_perm:[1,0,3,2] row_mask:0xf bank_mask:0xf bound_ctrl:1
	v_pk_fma_f32 v[6:7], v[2:3], v[86:87], v[10:11]
	v_cndmask_b32_e64 v202, v201, v200, s[38:39]
	v_add_f32_dpp v18, v18, v18 quad_perm:[2,3,0,1] row_mask:0xf bank_mask:0xf bound_ctrl:1
	ds_read_b128 v[44:47], v139 offset:11008
	v_add_f32_dpp v23, v202, v22 quad_perm:[1,0,3,2] row_mask:0xf bank_mask:0xf bound_ctrl:1
	v_add_f32_dpp v18, v18, v18 row_half_mirror row_mask:0xf bank_mask:0xf bound_ctrl:1
	ds_read_b128 v[40:43], v139 offset:10752
	s_nop 0
	v_add_f32_dpp v18, v18, v18 row_ror:8 row_mask:0xf bank_mask:0xf bound_ctrl:1
	ds_read_b128 v[48:51], v139 offset:11264
	v_pk_fma_f32 v[0:1], v[92:93], v[18:19], v[4:5] op_sel_hi:[1,0,1] neg_lo:[1,0,0] neg_hi:[1,0,0]
	v_pk_fma_f32 v[2:3], v[94:95], v[18:19], v[6:7] op_sel_hi:[1,0,1] neg_lo:[1,0,0] neg_hi:[1,0,0]
	ds_read_b128 v[56:59], v139 offset:11776
	s_waitcnt lgkmcnt(7)
	v_pk_mul_f32 v[8:9], v[118:119], v[126:127] op_sel_hi:[1,0]
	v_pk_mul_f32 v[10:11], v[120:121], v[126:127] op_sel_hi:[1,0]
	s_cmp_eq_u32 s4, 0
	s_cbranch_scc1 .Lscan_noy1
	global_store_dword v138, v23, s[96:97]
	v_add_u32_e32 v138, s90, v138

.Lscan_wd_1:
	ds_write_b128 v143, v[168:171]
	ds_write_b128 v143, v[172:175] offset:256
	ds_write_b128 v143, v[176:179] offset:512
	ds_write_b128 v143, v[180:183] offset:768
	ds_write_b128 v143, v[184:187] offset:1024
	ds_write_b32 v35, v167
	v_pk_mul_f32 v[16:17], v[0:1], v[110:111]
	v_pk_mul_f32 v[20:21], v[0:1], v[100:101]
	ds_read_b128 v[74:77], v139 offset:18240
	v_pk_fma_f32 v[16:17], v[2:3], v[112:113], v[16:17]
	v_pk_fma_f32 v[20:21], v[2:3], v[102:103], v[20:21]
	ds_read_b32 v82, v140 offset:17472
	v_add_f32_e32 v18, v16, v17
	v_pk_fma_f32 v[4:5], v[0:1], v[106:107], v[8:9]
	v_add_f32_e32 v194, v20, v21
	v_add_f32_dpp v18, v18, v18 quad_perm:[1,0,3,2] row_mask:0xf bank_mask:0xf bound_ctrl:1
	v_pk_fma_f32 v[6:7], v[2:3], v[108:109], v[10:11]
	s_nop 0
	v_add_f32_dpp v18, v18, v18 quad_perm:[2,3,0,1] row_mask:0xf bank_mask:0xf bound_ctrl:1
	ds_read_b128 v[66:69], v139 offset:17728
	v_add_f32_dpp v194, v194, v194 row_ror:8 row_mask:0xf bank_mask:0xc bound_ctrl:1
	v_add_f32_dpp v18, v18, v18 row_half_mirror row_mask:0xf bank_mask:0xf bound_ctrl:1
	ds_read_b128 v[62:65], v139 offset:17472
	v_add_f32_dpp v194, v14, v14 row_ror:8 row_mask:0xf bank_mask:0x3 bound_ctrl:1
	v_add_f32_dpp v18, v18, v18 row_ror:8 row_mask:0xf bank_mask:0xf bound_ctrl:1
	ds_read_b128 v[70:73], v139 offset:17984
	v_pk_fma_f32 v[0:1], v[114:115], v[18:19], v[4:5] op_sel_hi:[1,0,1] neg_lo:[1,0,0] neg_hi:[1,0,0]
	v_pk_fma_f32 v[2:3], v[116:117], v[18:19], v[6:7] op_sel_hi:[1,0,1] neg_lo:[1,0,0] neg_hi:[1,0,0]
	ds_read_b128 v[78:81], v139 offset:18496
	s_waitcnt lgkmcnt(7)
	v_pk_mul_f32 v[8:9], v[52:53], v[60:61] op_sel_hi:[1,0]
	v_pk_mul_f32 v[10:11], v[54:55], v[60:61] op_sel_hi:[1,0]
	v_pk_mul_f32 v[16:17], v[0:1], v[44:45]
	v_pk_mul_f32 v[20:21], v[0:1], v[122:123]
	ds_read_b128 v[96:99], v139 offset:19584
	v_pk_fma_f32 v[16:17], v[2:3], v[46:47], v[16:17]
	v_pk_fma_f32 v[20:21], v[2:3], v[124:125], v[20:21]
	ds_read_b32 v104, v140 offset:18816
	v_add_f32_e32 v18, v16, v17
	v_pk_fma_f32 v[4:5], v[0:1], v[40:41], v[8:9]
	v_add_f32_e32 v195, v20, v21
	v_add_f32_dpp v18, v18, v18 quad_perm:[1,0,3,2] row_mask:0xf bank_mask:0xf bound_ctrl:1
	v_pk_fma_f32 v[6:7], v[2:3], v[42:43], v[10:11]
	s_nop 0
	v_add_f32_dpp v18, v18, v18 quad_perm:[2,3,0,1] row_mask:0xf bank_mask:0xf bound_ctrl:1
	ds_read_b128 v[88:91], v139 offset:19072
	v_add_f32_dpp v195, v195, v195 row_ror:8 row_mask:0xf bank_mask:0xc bound_ctrl:1
	v_add_f32_dpp v18, v18, v18 row_half_mirror row_mask:0xf bank_mask:0xf bound_ctrl:1
	ds_read_b128 v[84:87], v139 offset:18816
	v_add_f32_dpp v195, v15, v15 row_ror:8 row_mask:0xf bank_mask:0x3 bound_ctrl:1
	v_add_f32_dpp v18, v18, v18 row_ror:8 row_mask:0xf bank_mask:0xf bound_ctrl:1
	ds_read_b128 v[92:95], v139 offset:19328
	v_pk_fma_f32 v[0:1], v[48:49], v[18:19], v[4:5] op_sel_hi:[1,0,1] neg_lo:[1,0,0] neg_hi:[1,0,0]
	v_pk_fma_f32 v[2:3], v[50:51], v[18:19], v[6:7] op_sel_hi:[1,0,1] neg_lo:[1,0,0] neg_hi:[1,0,0]
	ds_read_b128 v[100:103], v139 offset:19840
	s_waitcnt lgkmcnt(7)
	s_barrier
	s_add_i32 s0, s4, 3
	s_cmp_lt_u32 s0, s5
	s_cbranch_scc0 .Lscan_nold1
	s_mul_i32 s92, s0, s90
	v_add_u32_e32 v132, s92, v28
	v_add_u32_e32 v133, s92, v29
	v_add_u32_e32 v134, s92, v30
	v_add_u32_e32 v135, s92, v31
	v_add_u32_e32 v136, s92, v32
	v_add_u32_e32 v137, s92, v33
	global_load_dwordx4 v[168:171], v132, s[96:97]
	global_load_dwordx4 v[172:175], v133, s[96:97]
	global_load_dwordx4 v[176:179], v134, s[96:97]
	global_load_dwordx4 v[180:183], v135, s[96:97]
	global_load_dwordx4 v[184:187], v136, s[96:97]
	global_load_dword v167, v137, s[96:97]
.Lscan_nold1:
	v_pk_mul_f32 v[8:9], v[74:75], v[82:83] op_sel_hi:[1,0]
	v_pk_mul_f32 v[10:11], v[76:77], v[82:83] op_sel_hi:[1,0]
	v_pk_mul_f32 v[16:17], v[0:1], v[66:67]
	v_pk_mul_f32 v[20:21], v[0:1], v[56:57]
	ds_read_b128 v[118:121], v139 offset:20928
	v_pk_fma_f32 v[16:17], v[2:3], v[68:69], v[16:17]
	v_pk_fma_f32 v[20:21], v[2:3], v[58:59], v[20:21]
	ds_read_b32 v126, v140 offset:20160
	v_add_f32_e32 v18, v16, v17
	v_pk_fma_f32 v[4:5], v[0:1], v[62:63], v[8:9]
	v_add_f32_e32 v196, v20, v21
	v_add_f32_dpp v18, v18, v18 quad_perm:[1,0,3,2] row_mask:0xf bank_mask:0xf bound_ctrl:1
	v_pk_fma_f32 v[6:7], v[2:3], v[64:65], v[10:11]
	s_nop 0
	v_add_f32_dpp v18, v18, v18 quad_perm:[2,3,0,1] row_mask:0xf bank_mask:0xf bound_ctrl:1
	ds_read_b128 v[110:113], v139 offset:20416
	v_add_f32_dpp v196, v196, v196 row_ror:8 row_mask:0xf bank_mask:0xc bound_ctrl:1
	v_add_f32_dpp v18, v18, v18 row_half_mirror row_mask:0xf bank_mask:0xf bound_ctrl:1
	ds_read_b128 v[106:109], v139 offset:20160
	v_add_f32_dpp v196, v188, v188 row_ror:8 row_mask:0xf bank_mask:0x3 bound_ctrl:1
	v_add_f32_dpp v18, v18, v18 row_ror:8 row_mask:0xf bank_mask:0xf bound_ctrl:1
	ds_read_b128 v[114:117], v139 offset:20672
	v_pk_fma_f32 v[0:1], v[70:71], v[18:19], v[4:5] op_sel_hi:[1,0,1] neg_lo:[1,0,0] neg_hi:[1,0,0]
	v_pk_fma_f32 v[2:3], v[72:73], v[18:19], v[6:7] op_sel_hi:[1,0,1] neg_lo:[1,0,0] neg_hi:[1,0,0]
	ds_read_b128 v[122:125], v139 offset:21184
	s_waitcnt lgkmcnt(7)
	v_pk_mul_f32 v[8:9], v[96:97], v[104:105] op_sel_hi:[1,0]
	v_pk_mul_f32 v[10:11], v[98:99], v[104:105] op_sel_hi:[1,0]
	v_pk_mul_f32 v[16:17], v[0:1], v[88:89]
	v_pk_mul_f32 v[20:21], v[0:1], v[78:79]
	ds_read_b128 v[52:55], v141 offset:768
	v_pk_fma_f32 v[16:17], v[2:3], v[90:91], v[16:17]
	v_pk_fma_f32 v[20:21], v[2:3], v[80:81], v[20:21]
	ds_read_b32 v60, v142 offset:0
	v_add_f32_e32 v18, v16, v17
	v_pk_fma_f32 v[4:5], v[0:1], v[84:85], v[8:9]
	v_add_f32_e32 v197, v20, v21
	v_add_f32_dpp v18, v18, v18 quad_perm:[1,0,3,2] row_mask:0xf bank_mask:0xf bound_ctrl:1
	v_pk_fma_f32 v[6:7], v[2:3], v[86:87], v[10:11]
	s_nop 0
	v_add_f32_dpp v18, v18, v18 quad_perm:[2,3,0,1] row_mask:0xf bank_mask:0xf bound_ctrl:1
	ds_read_b128 v[44:47], v141 offset:256
	v_add_f32_dpp v197, v197, v197 row_ror:8 row_mask:0xf bank_mask:0xc bound_ctrl:1
	v_add_f32_dpp v18, v18, v18 row_half_mirror row_mask:0xf bank_mask:0xf bound_ctrl:1
	ds_read_b128 v[40:43], v141 offset:0
	v_add_f32_dpp v197, v189, v189 row_ror:8 row_mask:0xf bank_mask:0x3 bound_ctrl:1
	v_add_f32_dpp v18, v18, v18 row_ror:8 row_mask:0xf bank_mask:0xf bound_ctrl:1
	ds_read_b128 v[48:51], v141 offset:512
	v_pk_fma_f32 v[0:1], v[92:93], v[18:19], v[4:5] op_sel_hi:[1,0,1] neg_lo:[1,0,0] neg_hi:[1,0,0]
	v_pk_fma_f32 v[2:3], v[94:95], v[18:19], v[6:7] op_sel_hi:[1,0,1] neg_lo:[1,0,0] neg_hi:[1,0,0]
	ds_read_b128 v[56:59], v141 offset:1024
	s_waitcnt lgkmcnt(7)
	v_pk_mul_f32 v[8:9], v[118:119], v[126:127] op_sel_hi:[1,0]
	v_pk_mul_f32 v[10:11], v[120:121], v[126:127] op_sel_hi:[1,0]
	v_pk_mul_f32 v[16:17], v[0:1], v[110:111]
	v_pk_mul_f32 v[20:21], v[0:1], v[100:101]
	ds_read_b128 v[74:77], v141 offset:2112
	v_pk_fma_f32 v[16:17], v[2:3], v[112:113], v[16:17]
	v_pk_fma_f32 v[20:21], v[2:3], v[102:103], v[20:21]
	ds_read_b32 v82, v142 offset:1344
	v_add_f32_e32 v18, v16, v17
	v_pk_fma_f32 v[4:5], v[0:1], v[106:107], v[8:9]
	v_add_f32_e32 v200, v20, v21
	v_add_f32_dpp v18, v18, v18 quad_perm:[1,0,3,2] row_mask:0xf bank_mask:0xf bound_ctrl:1
	v_pk_fma_f32 v[6:7], v[2:3], v[108:109], v[10:11]
	s_nop 0
	v_add_f32_dpp v18, v18, v18 quad_perm:[2,3,0,1] row_mask:0xf bank_mask:0xf bound_ctrl:1
	ds_read_b128 v[66:69], v141 offset:1600
	v_add_f32_dpp v200, v200, v200 row_ror:8 row_mask:0xf bank_mask:0xc bound_ctrl:1
	v_add_f32_dpp v18, v18, v18 row_half_mirror row_mask:0xf bank_mask:0xf bound_ctrl:1
	ds_read_b128 v[62:65], v141 offset:1344
	v_add_f32_dpp v200, v190, v190 row_ror:8 row_mask:0xf bank_mask:0x3 bound_ctrl:1
	v_add_f32_dpp v18, v18, v18 row_ror:8 row_mask:0xf bank_mask:0xf bound_ctrl:1
	ds_read_b128 v[70:73], v141 offset:1856
	v_pk_fma_f32 v[0:1], v[114:115], v[18:19], v[4:5] op_sel_hi:[1,0,1] neg_lo:[1,0,0] neg_hi:[1,0,0]
	v_pk_fma_f32 v[2:3], v[116:117], v[18:19], v[6:7] op_sel_hi:[1,0,1] neg_lo:[1,0,0] neg_hi:[1,0,0]
	ds_read_b128 v[78:81], v141 offset:2368
	s_waitcnt lgkmcnt(7)
	v_pk_mul_f32 v[8:9], v[52:53], v[60:61] op_sel_hi:[1,0]
	v_pk_mul_f32 v[10:11], v[54:55], v[60:61] op_sel_hi:[1,0]
	s_add_i32 s4, s4, 1
	s_mov_b32 s0, s6
	s_mov_b32 s6, s7
	s_mov_b32 s7, s25
	s_mov_b32 s25, s0
	v_mov_b32_e32 v139, v141
	v_mov_b32_e32 v140, v142
	v_add_u32_e32 v141, s7, v24
	v_add_u32_e32 v142, s7, v25
	v_add_u32_e32 v143, s7, v26
	v_add_u32_e32 v35, s7, v27
	s_cmp_lt_u32 s4, s5
	s_cbranch_scc1 .Lscan_chunk
	v_mul_f32_e32 v201, v0, v122
	v_fmac_f32_e32 v201, v1, v123
	v_fmac_f32_e32 v201, v2, v124
	v_fmac_f32_e32 v201, v3, v125
	s_nop 1
	v_add_f32_dpp v201, v201, v201 row_ror:8 row_mask:0xf bank_mask:0xc bound_ctrl:1
	v_add_f32_dpp v201, v191, v191 row_ror:8 row_mask:0xf bank_mask:0x3 bound_ctrl:1
	s_nop 1
	v_add_f32_dpp v196, v196, v196 row_half_mirror row_mask:0xf bank_mask:0xa bound_ctrl:1
	v_add_f32_dpp v196, v192, v192 row_half_mirror row_mask:0xf bank_mask:0x5 bound_ctrl:1
	v_add_f32_dpp v197, v197, v197 row_half_mirror row_mask:0xf bank_mask:0xa bound_ctrl:1
	v_add_f32_dpp v197, v193, v193 row_half_mirror row_mask:0xf bank_mask:0x5 bound_ctrl:1
	v_add_f32_dpp v200, v200, v200 row_half_mirror row_mask:0xf bank_mask:0xa bound_ctrl:1
	v_add_f32_dpp v200, v194, v194 row_half_mirror row_mask:0xf bank_mask:0x5 bound_ctrl:1
	v_add_f32_dpp v201, v201, v201 row_half_mirror row_mask:0xf bank_mask:0xa bound_ctrl:1
	v_add_f32_dpp v201, v195, v195 row_half_mirror row_mask:0xf bank_mask:0x5 bound_ctrl:1
	s_nop 1
	v_cndmask_b32_e64 v22, v196, v200, s[36:37]
	v_cndmask_b32_e64 v202, v200, v196, s[36:37]
	s_nop 1
	v_add_f32_dpp v200, v202, v22 quad_perm:[2,3,0,1] row_mask:0xf bank_mask:0xf bound_ctrl:1
	v_cndmask_b32_e64 v203, v197, v201, s[36:37]
	v_cndmask_b32_e64 v202, v201, v197, s[36:37]
	s_nop 1
	v_add_f32_dpp v201, v202, v203 quad_perm:[2,3,0,1] row_mask:0xf bank_mask:0xf bound_ctrl:1
	v_cndmask_b32_e64 v22, v200, v201, s[38:39]
	v_cndmask_b32_e64 v202, v201, v200, s[38:39]
	s_nop 1
	v_add_f32_dpp v23, v202, v22 quad_perm:[1,0,3,2] row_mask:0xf bank_mask:0xf bound_ctrl:1
	global_store_dword v138, v23, s[96:97]
	s_cmp_eq_u32 s28, 0
	s_cbranch_scc1 .Lscan_done
	v_readlane_b32 s0, v254, 57
	v_readlane_b32 s1, v254, 58
	s_nop 4
	global_store_dwordx4 v39, v[0:3], s[0:1]
